# streaming (nt) stores for the f32 residual stream written by the out-projection epilogue (re-read only by the down-projection epilogue); nt loads of it there
# speedup vs baseline: 1.0568x; 1.0031x over previous
; __device__ __forceinline__ unsigned cvt_pk_bf16(float lo, float hi) { unsigned r; asm volatile("v_cvt_pk_bf16_f32 %0, %1, %2" : "=v"(r) : "v"(lo), "v"(hi)); return r; }
;     __device__ __forceinline__ void fused(f32x4 (&acc)[2][2][4][2], const Unit& u, int wr, int wc, int fr, int fq, PG8_LAS unsigned char* lds, int wid, int lane) const {
;     ...
;             f32x4 g[2][2], sv[2][2];
; #pragma unroll
;             for (int bj = 0; bj < 2; ++bj)
; #pragma unroll
;                 for (int n = 0; n < 2; ++n) { g[bj][n] = *(const f32x4*)(gv2 + col0 + bj * HALF + n * 16); sv[bj][n] = *(const f32x4*)(sv2 + col0 + bj * HALF + n * 16); }
; #pragma unroll
;             for (int ai = 0; ai < 2; ++ai)
; #pragma unroll
;                 for (int m = 0; m < 4; ++m) { const int r = ai * HALF + wr * 64 + m * 16 + fr; const float rs = S[r]; const size_t off = (size_t)(row_off + u.pm * BM + r) * DM + col0;
; #pragma unroll
;                     for (int bj = 0; bj < 2; ++bj)
; #pragma unroll
;                         for (int n = 0; n < 2; ++n) { const f32x4 x1 = acc[ai][bj][m][n]; *(f32x4*)(out + off + bj * HALF + n * 16) = x1;
;                             const f32x4 o = x1 * rs * g[bj][n] + sv[bj][n]; u32x2 w; w.x = cvt_pk_bf16(o[0], o[1]); w.y = cvt_pk_bf16(o[2], o[3]); *(u32x2*)(xn + off + bj * HALF + n * 16) = w; }
;                     asm volatile("" ::: "memory"); }
.LBB0_735:
	s_or_b64 exec, exec, s[10:11]
	s_waitcnt lgkmcnt(0)
	v_lshl_add_u64 v[128:129], v[166:167], 2, s[52:53]
	v_add_co_u32_e32 v152, vcc, s66, v128
	s_waitcnt lgkmcnt(0)
	s_barrier
	s_nop 0
	v_addc_co_u32_e32 v153, vcc, 0, v129, vcc
	v_add_co_u32_e32 v156, vcc, s35, v128
	v_lshl_add_u64 v[130:131], v[128:129], 0, s[42:43]
	v_lshl_add_u64 v[132:133], v[128:129], 0, s[44:45]
	v_addc_co_u32_e32 v157, vcc, 0, v129, vcc
	global_load_dwordx4 v[144:147], v[132:133], off offset:64
	global_load_dwordx4 v[148:151], v[130:131], off offset:64
	global_load_dwordx4 v[136:139], v[130:131], off offset:512
	global_load_dwordx4 v[140:143], v[132:133], off offset:512
	s_nop 0
	global_load_dwordx4 v[128:131], v[130:131], off offset:576
	s_nop 0
	global_load_dwordx4 v[132:135], v[132:133], off offset:576
	s_nop 0
	global_load_dwordx4 v[152:155], v[152:153], off
	s_nop 0
	global_load_dwordx4 v[156:159], v[156:157], off
	ds_read_b32 v188, v160 offset:4096
	v_lshlrev_b64 v[178:179], 10, v[178:179]
	v_lshl_add_u64 v[178:179], v[178:179], 0, v[166:167]
	v_lshl_add_u64 v[190:191], v[178:179], 2, s[12:13]
	s_add_u32 s6, s14, 0x2000000
	global_store_dwordx4 v[190:191], v[124:127], off nt
	s_addc_u32 s7, s15, 0
	v_lshl_add_u64 v[178:179], v[178:179], 1, s[6:7]
	s_waitcnt lgkmcnt(0)
	v_pk_mul_f32 v[124:125], v[124:125], v[188:189] op_sel_hi:[1,0]
	v_pk_mul_f32 v[126:127], v[126:127], v[188:189] op_sel_hi:[1,0]
	v_pk_mul_f32 v[192:193], v[122:123], v[188:189] op_sel_hi:[1,0]
	v_pk_mul_f32 v[196:197], v[120:121], v[188:189] op_sel_hi:[1,0]
	v_pk_mul_f32 v[198:199], v[118:119], v[188:189] op_sel_hi:[1,0]
	v_pk_mul_f32 v[200:201], v[116:117], v[188:189] op_sel_hi:[1,0]
	v_pk_mul_f32 v[202:203], v[114:115], v[188:189] op_sel_hi:[1,0]
	v_pk_mul_f32 v[188:189], v[112:113], v[188:189] op_sel_hi:[1,0]
	v_lshlrev_b64 v[176:177], 10, v[176:177]
	s_waitcnt vmcnt(7)
	v_pk_fma_f32 v[192:193], v[150:151], v[192:193], v[146:147]
	v_pk_fma_f32 v[196:197], v[148:149], v[196:197], v[144:145]
	s_waitcnt vmcnt(5)
	v_pk_fma_f32 v[198:199], v[138:139], v[198:199], v[142:143]
	v_pk_fma_f32 v[200:201], v[136:137], v[200:201], v[140:141]
	s_waitcnt vmcnt(3)
	v_pk_fma_f32 v[202:203], v[130:131], v[202:203], v[134:135]
	v_pk_fma_f32 v[188:189], v[128:129], v[188:189], v[132:133]
	s_waitcnt vmcnt(1)
	v_pk_fma_f32 v[124:125], v[152:153], v[124:125], v[156:157]
	v_pk_fma_f32 v[126:127], v[154:155], v[126:127], v[158:159]
	v_cvt_pk_bf16_f32 v124, v124, v125
	s_nop 0
	v_cvt_pk_bf16_f32 v125, v126, v127
	global_store_dwordx2 v[178:179], v[124:125], off
	global_store_dwordx4 v[190:191], v[120:123], off offset:64 nt
	s_nop 1
	v_cvt_pk_bf16_f32 v120, v196, v197
	v_cvt_pk_bf16_f32 v121, v192, v193
	global_store_dwordx2 v[178:179], v[120:121], off offset:32
	global_store_dwordx4 v[190:191], v[116:119], off offset:512 nt
	s_nop 1
	v_cvt_pk_bf16_f32 v116, v200, v201
	v_cvt_pk_bf16_f32 v117, v198, v199
	global_store_dwordx2 v[178:179], v[116:117], off offset:256
	global_store_dwordx4 v[190:191], v[112:115], off offset:576 nt
	s_nop 1
	v_cvt_pk_bf16_f32 v112, v188, v189
	v_cvt_pk_bf16_f32 v113, v202, v203
	global_store_dwordx2 v[178:179], v[112:113], off offset:288
	ds_read_b32 v112, v160 offset:4160
	v_lshl_add_u64 v[114:115], v[176:177], 0, v[166:167]
	v_lshl_add_u64 v[116:117], v[114:115], 2, s[12:13]
	global_store_dwordx4 v[116:117], v[108:111], off nt
	v_lshl_add_u64 v[114:115], v[114:115], 1, s[6:7]
	s_waitcnt lgkmcnt(0)
	v_pk_mul_f32 v[118:119], v[106:107], v[112:113] op_sel_hi:[1,0]
	v_pk_mul_f32 v[108:109], v[108:109], v[112:113] op_sel_hi:[1,0]
	v_pk_mul_f32 v[110:111], v[110:111], v[112:113] op_sel_hi:[1,0]
	v_pk_fma_f32 v[108:109], v[152:153], v[108:109], v[156:157]
	v_pk_mul_f32 v[120:121], v[104:105], v[112:113] op_sel_hi:[1,0]
	v_pk_fma_f32 v[110:111], v[154:155], v[110:111], v[158:159]
	v_cvt_pk_bf16_f32 v108, v108, v109
	v_pk_mul_f32 v[122:123], v[102:103], v[112:113] op_sel_hi:[1,0]
	v_cvt_pk_bf16_f32 v109, v110, v111
	v_pk_mul_f32 v[124:125], v[100:101], v[112:113] op_sel_hi:[1,0]
	v_pk_fma_f32 v[118:119], v[150:151], v[118:119], v[146:147]
	v_pk_fma_f32 v[120:121], v[148:149], v[120:121], v[144:145]
	global_store_dwordx2 v[114:115], v[108:109], off
	global_store_dwordx4 v[116:117], v[104:107], off offset:64 nt
	v_pk_mul_f32 v[126:127], v[98:99], v[112:113] op_sel_hi:[1,0]
	v_pk_mul_f32 v[112:113], v[96:97], v[112:113] op_sel_hi:[1,0]
	v_cvt_pk_bf16_f32 v104, v120, v121
	v_cvt_pk_bf16_f32 v105, v118, v119
	v_pk_fma_f32 v[122:123], v[138:139], v[122:123], v[142:143]
	v_pk_fma_f32 v[124:125], v[136:137], v[124:125], v[140:141]
	global_store_dwordx2 v[114:115], v[104:105], off offset:32
	global_store_dwordx4 v[116:117], v[100:103], off offset:512 nt
	v_pk_fma_f32 v[126:127], v[130:131], v[126:127], v[134:135]
	v_pk_fma_f32 v[112:113], v[128:129], v[112:113], v[132:133]
	v_cvt_pk_bf16_f32 v100, v124, v125
	v_cvt_pk_bf16_f32 v101, v122, v123
	global_store_dwordx2 v[114:115], v[100:101], off offset:256
	global_store_dwordx4 v[116:117], v[96:99], off offset:576 nt
	s_nop 1
	v_cvt_pk_bf16_f32 v96, v112, v113
	v_cvt_pk_bf16_f32 v97, v126, v127
	global_store_dwordx2 v[114:115], v[96:97], off offset:288
	ds_read_b32 v96, v160 offset:4224
	v_lshlrev_b64 v[98:99], 10, v[168:169]
	v_lshl_add_u64 v[98:99], v[98:99], 0, v[166:167]
	v_lshl_add_u64 v[100:101], v[98:99], 2, s[12:13]
	global_store_dwordx4 v[100:101], v[92:95], off nt
	s_waitcnt lgkmcnt(0)
; __device__ __forceinline__ unsigned cvt_pk_bf16(float lo, float hi) { unsigned r; asm volatile("v_cvt_pk_bf16_f32 %0, %1, %2" : "=v"(r) : "v"(lo), "v"(hi)); return r; }
;     __device__ __forceinline__ void fused(f32x4 (&acc)[2][2][4][2], const Unit& u, int wr, int wc, int fr, int fq, PG8_LAS unsigned char* lds, int wid, int lane) const {
;     ...
;             for (int ai = 0; ai < 2; ++ai)
; #pragma unroll
;                 for (int m = 0; m < 4; ++m) { const int r = ai * HALF + wr * 64 + m * 16 + fr; const float rs = S[r]; const size_t off = (size_t)(row_off + u.pm * BM + r) * DM + col0;
; #pragma unroll
;                     for (int bj = 0; bj < 2; ++bj)
; #pragma unroll
;                         for (int n = 0; n < 2; ++n) { const f32x4 x1 = acc[ai][bj][m][n]; *(f32x4*)(out + off + bj * HALF + n * 16) = x1;
;                             const f32x4 o = x1 * rs * g[bj][n] + sv[bj][n]; u32x2 w; w.x = cvt_pk_bf16(o[0], o[1]); w.y = cvt_pk_bf16(o[2], o[3]); *(u32x2*)(xn + off + bj * HALF + n * 16) = w; }
;                     asm volatile("" ::: "memory"); }
	s_nop 0
	v_pk_mul_f32 v[94:95], v[94:95], v[96:97] op_sel_hi:[1,0]
	v_pk_mul_f32 v[92:93], v[92:93], v[96:97] op_sel_hi:[1,0]
	v_pk_fma_f32 v[94:95], v[154:155], v[94:95], v[158:159]
	v_pk_fma_f32 v[92:93], v[152:153], v[92:93], v[156:157]
	s_nop 0
	v_cvt_pk_bf16_f32 v92, v92, v93
	v_cvt_pk_bf16_f32 v93, v94, v95
	v_lshl_add_u64 v[94:95], v[98:99], 1, s[6:7]
	global_store_dwordx2 v[94:95], v[92:93], off
	global_store_dwordx4 v[100:101], v[88:91], off offset:64 nt
	s_nop 1
	v_pk_mul_f32 v[88:89], v[88:89], v[96:97] op_sel_hi:[1,0]
	v_pk_mul_f32 v[90:91], v[90:91], v[96:97] op_sel_hi:[1,0]
	v_pk_fma_f32 v[88:89], v[148:149], v[88:89], v[144:145]
	v_pk_fma_f32 v[90:91], v[150:151], v[90:91], v[146:147]
	v_cvt_pk_bf16_f32 v88, v88, v89
	s_nop 0
	v_cvt_pk_bf16_f32 v89, v90, v91
	global_store_dwordx2 v[94:95], v[88:89], off offset:32
	global_store_dwordx4 v[100:101], v[84:87], off offset:512 nt
	s_nop 1
	v_pk_mul_f32 v[84:85], v[84:85], v[96:97] op_sel_hi:[1,0]
	v_pk_mul_f32 v[86:87], v[86:87], v[96:97] op_sel_hi:[1,0]
	v_pk_fma_f32 v[84:85], v[136:137], v[84:85], v[140:141]
	v_pk_fma_f32 v[86:87], v[138:139], v[86:87], v[142:143]
	v_cvt_pk_bf16_f32 v84, v84, v85
	s_nop 0
	v_cvt_pk_bf16_f32 v85, v86, v87
	global_store_dwordx2 v[94:95], v[84:85], off offset:256
	global_store_dwordx4 v[100:101], v[80:83], off offset:576 nt
	s_nop 1
	v_pk_mul_f32 v[80:81], v[80:81], v[96:97] op_sel_hi:[1,0]
	v_pk_mul_f32 v[82:83], v[82:83], v[96:97] op_sel_hi:[1,0]
	v_pk_fma_f32 v[80:81], v[128:129], v[80:81], v[132:133]
	v_pk_fma_f32 v[82:83], v[130:131], v[82:83], v[134:135]
	v_cvt_pk_bf16_f32 v80, v80, v81
	s_nop 0
	v_cvt_pk_bf16_f32 v81, v82, v83
	global_store_dwordx2 v[94:95], v[80:81], off offset:288
	ds_read_b32 v80, v160 offset:4288
	v_lshlrev_b64 v[82:83], 10, v[170:171]
	v_lshl_add_u64 v[82:83], v[82:83], 0, v[166:167]
	v_lshl_add_u64 v[84:85], v[82:83], 2, s[12:13]
	global_store_dwordx4 v[84:85], v[76:79], off nt
	s_waitcnt lgkmcnt(0)
	s_nop 0
	v_pk_mul_f32 v[78:79], v[78:79], v[80:81] op_sel_hi:[1,0]
	v_pk_mul_f32 v[76:77], v[76:77], v[80:81] op_sel_hi:[1,0]
	v_pk_fma_f32 v[78:79], v[154:155], v[78:79], v[158:159]
	v_pk_fma_f32 v[76:77], v[152:153], v[76:77], v[156:157]
	s_nop 0
	v_cvt_pk_bf16_f32 v76, v76, v77
	v_cvt_pk_bf16_f32 v77, v78, v79
	v_lshl_add_u64 v[78:79], v[82:83], 1, s[6:7]
	global_store_dwordx2 v[78:79], v[76:77], off
	global_store_dwordx4 v[84:85], v[72:75], off offset:64 nt
	s_nop 1
	v_pk_mul_f32 v[72:73], v[72:73], v[80:81] op_sel_hi:[1,0]
	v_pk_mul_f32 v[74:75], v[74:75], v[80:81] op_sel_hi:[1,0]
	v_pk_fma_f32 v[72:73], v[148:149], v[72:73], v[144:145]
	v_pk_fma_f32 v[74:75], v[150:151], v[74:75], v[146:147]
	v_cvt_pk_bf16_f32 v72, v72, v73
	s_nop 0
	v_cvt_pk_bf16_f32 v73, v74, v75
	global_store_dwordx2 v[78:79], v[72:73], off offset:32
	global_store_dwordx4 v[84:85], v[68:71], off offset:512 nt
	s_nop 1
	v_pk_mul_f32 v[68:69], v[68:69], v[80:81] op_sel_hi:[1,0]
	v_pk_mul_f32 v[70:71], v[70:71], v[80:81] op_sel_hi:[1,0]
	v_pk_fma_f32 v[68:69], v[136:137], v[68:69], v[140:141]
	v_pk_fma_f32 v[70:71], v[138:139], v[70:71], v[142:143]
	v_cvt_pk_bf16_f32 v68, v68, v69
	s_nop 0
	v_cvt_pk_bf16_f32 v69, v70, v71
	global_store_dwordx2 v[78:79], v[68:69], off offset:256
	global_store_dwordx4 v[84:85], v[64:67], off offset:576 nt
	s_nop 1
	v_pk_mul_f32 v[64:65], v[64:65], v[80:81] op_sel_hi:[1,0]
	v_pk_mul_f32 v[66:67], v[66:67], v[80:81] op_sel_hi:[1,0]
	v_pk_fma_f32 v[64:65], v[128:129], v[64:65], v[132:133]
	v_pk_fma_f32 v[66:67], v[130:131], v[66:67], v[134:135]
	v_cvt_pk_bf16_f32 v64, v64, v65
	s_nop 0
	v_cvt_pk_bf16_f32 v65, v66, v67
	global_store_dwordx2 v[78:79], v[64:65], off offset:288
	ds_read_b32 v64, v160 offset:4608
	v_lshlrev_b64 v[66:67], 10, v[172:173]
	v_lshl_add_u64 v[66:67], v[66:67], 0, v[166:167]
	v_lshl_add_u64 v[68:69], v[66:67], 2, s[12:13]
	global_store_dwordx4 v[68:69], v[60:63], off nt
	s_waitcnt lgkmcnt(0)
	s_nop 0
	v_pk_mul_f32 v[62:63], v[62:63], v[64:65] op_sel_hi:[1,0]
	v_pk_mul_f32 v[60:61], v[60:61], v[64:65] op_sel_hi:[1,0]
	v_pk_fma_f32 v[62:63], v[154:155], v[62:63], v[158:159]
	v_pk_fma_f32 v[60:61], v[152:153], v[60:61], v[156:157]
	s_nop 0
	v_cvt_pk_bf16_f32 v60, v60, v61
	v_cvt_pk_bf16_f32 v61, v62, v63
	v_lshl_add_u64 v[62:63], v[66:67], 1, s[6:7]
	global_store_dwordx2 v[62:63], v[60:61], off
	global_store_dwordx4 v[68:69], v[56:59], off offset:64 nt
	s_nop 1
	v_pk_mul_f32 v[56:57], v[56:57], v[64:65] op_sel_hi:[1,0]
	v_pk_mul_f32 v[58:59], v[58:59], v[64:65] op_sel_hi:[1,0]
	v_pk_fma_f32 v[56:57], v[148:149], v[56:57], v[144:145]
	v_pk_fma_f32 v[58:59], v[150:151], v[58:59], v[146:147]
	v_cvt_pk_bf16_f32 v56, v56, v57
	s_nop 0
	v_cvt_pk_bf16_f32 v57, v58, v59
	global_store_dwordx2 v[62:63], v[56:57], off offset:32
	global_store_dwordx4 v[68:69], v[52:55], off offset:512 nt
	s_nop 1
	v_pk_mul_f32 v[52:53], v[52:53], v[64:65] op_sel_hi:[1,0]
	v_pk_mul_f32 v[54:55], v[54:55], v[64:65] op_sel_hi:[1,0]
	v_pk_fma_f32 v[52:53], v[136:137], v[52:53], v[140:141]
	v_pk_fma_f32 v[54:55], v[138:139], v[54:55], v[142:143]
	v_cvt_pk_bf16_f32 v52, v52, v53
	s_nop 0
	v_cvt_pk_bf16_f32 v53, v54, v55
	global_store_dwordx2 v[62:63], v[52:53], off offset:256
	global_store_dwordx4 v[68:69], v[48:51], off offset:576 nt
	s_nop 1
	v_pk_mul_f32 v[48:49], v[48:49], v[64:65] op_sel_hi:[1,0]
	v_pk_mul_f32 v[50:51], v[50:51], v[64:65] op_sel_hi:[1,0]
	v_pk_fma_f32 v[48:49], v[128:129], v[48:49], v[132:133]
	v_pk_fma_f32 v[50:51], v[130:131], v[50:51], v[134:135]
	v_cvt_pk_bf16_f32 v48, v48, v49
	s_nop 0
	v_cvt_pk_bf16_f32 v49, v50, v51
	global_store_dwordx2 v[62:63], v[48:49], off offset:288
	ds_read_b32 v48, v160 offset:4672
	v_lshlrev_b64 v[50:51], 10, v[174:175]
	v_lshl_add_u64 v[50:51], v[50:51], 0, v[166:167]
	v_lshl_add_u64 v[52:53], v[50:51], 2, s[12:13]
	global_store_dwordx4 v[52:53], v[44:47], off nt
	s_waitcnt lgkmcnt(0)
; __device__ __forceinline__ unsigned cvt_pk_bf16(float lo, float hi) { unsigned r; asm volatile("v_cvt_pk_bf16_f32 %0, %1, %2" : "=v"(r) : "v"(lo), "v"(hi)); return r; }
;     __device__ __forceinline__ void fused(f32x4 (&acc)[2][2][4][2], const Unit& u, int wr, int wc, int fr, int fq, PG8_LAS unsigned char* lds, int wid, int lane) const {
;     ...
;             for (int ai = 0; ai < 2; ++ai)
; #pragma unroll
;                 for (int m = 0; m < 4; ++m) { const int r = ai * HALF + wr * 64 + m * 16 + fr; const float rs = S[r]; const size_t off = (size_t)(row_off + u.pm * BM + r) * DM + col0;
; #pragma unroll
;                     for (int bj = 0; bj < 2; ++bj)
; #pragma unroll
;                         for (int n = 0; n < 2; ++n) { const f32x4 x1 = acc[ai][bj][m][n]; *(f32x4*)(out + off + bj * HALF + n * 16) = x1;
;                             const f32x4 o = x1 * rs * g[bj][n] + sv[bj][n]; u32x2 w; w.x = cvt_pk_bf16(o[0], o[1]); w.y = cvt_pk_bf16(o[2], o[3]); *(u32x2*)(xn + off + bj * HALF + n * 16) = w; }
;                     asm volatile("" ::: "memory"); }
	s_nop 0
	v_pk_mul_f32 v[46:47], v[46:47], v[48:49] op_sel_hi:[1,0]
	v_pk_mul_f32 v[44:45], v[44:45], v[48:49] op_sel_hi:[1,0]
	v_pk_fma_f32 v[46:47], v[154:155], v[46:47], v[158:159]
	v_pk_fma_f32 v[44:45], v[152:153], v[44:45], v[156:157]
	s_nop 0
	v_cvt_pk_bf16_f32 v44, v44, v45
	v_cvt_pk_bf16_f32 v45, v46, v47
	v_lshl_add_u64 v[46:47], v[50:51], 1, s[6:7]
	global_store_dwordx2 v[46:47], v[44:45], off
	global_store_dwordx4 v[52:53], v[40:43], off offset:64 nt
	s_nop 1
	v_pk_mul_f32 v[40:41], v[40:41], v[48:49] op_sel_hi:[1,0]
	v_pk_mul_f32 v[42:43], v[42:43], v[48:49] op_sel_hi:[1,0]
	v_pk_fma_f32 v[40:41], v[148:149], v[40:41], v[144:145]
	v_pk_fma_f32 v[42:43], v[150:151], v[42:43], v[146:147]
	v_cvt_pk_bf16_f32 v40, v40, v41
	s_nop 0
	v_cvt_pk_bf16_f32 v41, v42, v43
	global_store_dwordx2 v[46:47], v[40:41], off offset:32
	global_store_dwordx4 v[52:53], v[36:39], off offset:512 nt
	s_nop 1
	v_pk_mul_f32 v[36:37], v[36:37], v[48:49] op_sel_hi:[1,0]
	v_pk_mul_f32 v[38:39], v[38:39], v[48:49] op_sel_hi:[1,0]
	v_pk_fma_f32 v[36:37], v[136:137], v[36:37], v[140:141]
	v_pk_fma_f32 v[38:39], v[138:139], v[38:39], v[142:143]
	v_cvt_pk_bf16_f32 v36, v36, v37
	s_nop 0
	v_cvt_pk_bf16_f32 v37, v38, v39
	global_store_dwordx2 v[46:47], v[36:37], off offset:256
	global_store_dwordx4 v[52:53], v[32:35], off offset:576 nt
	s_nop 1
	v_pk_mul_f32 v[32:33], v[32:33], v[48:49] op_sel_hi:[1,0]
	v_pk_mul_f32 v[34:35], v[34:35], v[48:49] op_sel_hi:[1,0]
	v_pk_fma_f32 v[32:33], v[128:129], v[32:33], v[132:133]
	v_pk_fma_f32 v[34:35], v[130:131], v[34:35], v[134:135]
	v_cvt_pk_bf16_f32 v32, v32, v33
	s_nop 0
	v_cvt_pk_bf16_f32 v33, v34, v35
	global_store_dwordx2 v[46:47], v[32:33], off offset:288
	ds_read_b32 v32, v160 offset:4736
	v_lshlrev_b64 v[34:35], 10, v[180:181]
	v_lshl_add_u64 v[34:35], v[34:35], 0, v[166:167]
	v_lshl_add_u64 v[36:37], v[34:35], 2, s[12:13]
	global_store_dwordx4 v[36:37], v[28:31], off nt
	s_waitcnt lgkmcnt(0)
	s_nop 0
	v_pk_mul_f32 v[30:31], v[30:31], v[32:33] op_sel_hi:[1,0]
	v_pk_mul_f32 v[28:29], v[28:29], v[32:33] op_sel_hi:[1,0]
	v_pk_fma_f32 v[30:31], v[154:155], v[30:31], v[158:159]
	v_pk_fma_f32 v[28:29], v[152:153], v[28:29], v[156:157]
	s_nop 0
	v_cvt_pk_bf16_f32 v28, v28, v29
	v_cvt_pk_bf16_f32 v29, v30, v31
	v_lshl_add_u64 v[30:31], v[34:35], 1, s[6:7]
	global_store_dwordx2 v[30:31], v[28:29], off
	global_store_dwordx4 v[36:37], v[24:27], off offset:64 nt
	s_nop 1
	v_pk_mul_f32 v[24:25], v[24:25], v[32:33] op_sel_hi:[1,0]
	v_pk_mul_f32 v[26:27], v[26:27], v[32:33] op_sel_hi:[1,0]
	v_pk_fma_f32 v[24:25], v[148:149], v[24:25], v[144:145]
	v_pk_fma_f32 v[26:27], v[150:151], v[26:27], v[146:147]
	v_cvt_pk_bf16_f32 v24, v24, v25
	s_nop 0
	v_cvt_pk_bf16_f32 v25, v26, v27
	global_store_dwordx2 v[30:31], v[24:25], off offset:32
	global_store_dwordx4 v[36:37], v[20:23], off offset:512 nt
	s_nop 1
	v_pk_mul_f32 v[20:21], v[20:21], v[32:33] op_sel_hi:[1,0]
	v_pk_mul_f32 v[22:23], v[22:23], v[32:33] op_sel_hi:[1,0]
	v_pk_fma_f32 v[20:21], v[136:137], v[20:21], v[140:141]
	v_pk_fma_f32 v[22:23], v[138:139], v[22:23], v[142:143]
	v_cvt_pk_bf16_f32 v20, v20, v21
	s_nop 0
	v_cvt_pk_bf16_f32 v21, v22, v23
	global_store_dwordx2 v[30:31], v[20:21], off offset:256
	global_store_dwordx4 v[36:37], v[16:19], off offset:576 nt
	s_nop 1
	v_pk_mul_f32 v[16:17], v[16:17], v[32:33] op_sel_hi:[1,0]
	v_pk_mul_f32 v[18:19], v[18:19], v[32:33] op_sel_hi:[1,0]
	v_pk_fma_f32 v[16:17], v[128:129], v[16:17], v[132:133]
	v_pk_fma_f32 v[18:19], v[130:131], v[18:19], v[134:135]
	v_cvt_pk_bf16_f32 v16, v16, v17
	s_nop 0
	v_cvt_pk_bf16_f32 v17, v18, v19
	global_store_dwordx2 v[30:31], v[16:17], off offset:288
	ds_read_b32 v16, v160 offset:4800
	v_lshlrev_b64 v[18:19], 10, v[182:183]
	v_lshl_add_u64 v[18:19], v[18:19], 0, v[166:167]
	v_lshl_add_u64 v[20:21], v[18:19], 2, s[12:13]
	global_store_dwordx4 v[20:21], v[12:15], off nt
	s_waitcnt lgkmcnt(0)
	s_nop 0
	v_pk_mul_f32 v[14:15], v[14:15], v[16:17] op_sel_hi:[1,0]
	v_pk_mul_f32 v[12:13], v[12:13], v[16:17] op_sel_hi:[1,0]
	v_pk_fma_f32 v[14:15], v[154:155], v[14:15], v[158:159]
	v_pk_fma_f32 v[12:13], v[152:153], v[12:13], v[156:157]
	s_nop 0
	v_cvt_pk_bf16_f32 v12, v12, v13
	v_cvt_pk_bf16_f32 v13, v14, v15
	v_lshl_add_u64 v[14:15], v[18:19], 1, s[6:7]
	global_store_dwordx2 v[14:15], v[12:13], off
	global_store_dwordx4 v[20:21], v[8:11], off offset:64 nt
	s_nop 1
	v_pk_mul_f32 v[8:9], v[8:9], v[16:17] op_sel_hi:[1,0]
	v_pk_mul_f32 v[10:11], v[10:11], v[16:17] op_sel_hi:[1,0]
	v_pk_fma_f32 v[8:9], v[148:149], v[8:9], v[144:145]
	v_pk_fma_f32 v[10:11], v[150:151], v[10:11], v[146:147]
	v_cvt_pk_bf16_f32 v8, v8, v9
	s_nop 0
	v_cvt_pk_bf16_f32 v9, v10, v11
	global_store_dwordx2 v[14:15], v[8:9], off offset:32
	global_store_dwordx4 v[20:21], v[4:7], off offset:512 nt
	s_nop 1
	v_pk_mul_f32 v[4:5], v[4:5], v[16:17] op_sel_hi:[1,0]
	v_pk_mul_f32 v[6:7], v[6:7], v[16:17] op_sel_hi:[1,0]
	v_pk_fma_f32 v[4:5], v[136:137], v[4:5], v[140:141]
	v_pk_fma_f32 v[6:7], v[138:139], v[6:7], v[142:143]
	v_cvt_pk_bf16_f32 v4, v4, v5
	s_nop 0
	v_cvt_pk_bf16_f32 v5, v6, v7
	global_store_dwordx2 v[14:15], v[4:5], off offset:256
	global_store_dwordx4 v[20:21], v[0:3], off offset:576 nt
	s_nop 1
	v_pk_mul_f32 v[0:1], v[0:1], v[16:17] op_sel_hi:[1,0]
	v_pk_mul_f32 v[2:3], v[2:3], v[16:17] op_sel_hi:[1,0]
	v_pk_fma_f32 v[0:1], v[128:129], v[0:1], v[132:133]
	v_pk_fma_f32 v[2:3], v[130:131], v[2:3], v[134:135]
	v_cvt_pk_bf16_f32 v0, v0, v1
	s_nop 0
	v_cvt_pk_bf16_f32 v1, v2, v3
	global_store_dwordx2 v[14:15], v[0:1], off offset:288
	s_waitcnt lgkmcnt(0)
	s_barrier

; #define PG8_LAS __attribute__((address_space(3)))
;     __device__ __forceinline__ void fused(f32x4 (&acc)[2][2][4][2], const Unit& u, int wr, int wc, int fr, int fq, PG8_LAS unsigned char* lds, int wid, int lane) const {
;         const PG8_LAS float* S = (const PG8_LAS float*)(lds + 4096);
;         const int col0 = u.pn * BM + wc * 32 + 4 * fq;
;         st.run(acc, u, wr, wc, fr, fq, lds, wid, lane);
;         f32x4 g[2][2];
; #pragma unroll
;         for (int bj = 0; bj < 2; ++bj)
; #pragma unroll
;             for (int n = 0; n < 2; ++n) g[bj][n] = *(const f32x4*)(gv + col0 + bj * HALF + n * 16);
; #pragma unroll
;         for (int ai = 0; ai < 2; ++ai)
; #pragma unroll
;             for (int m = 0; m < 4; ++m) { const int r = ai * HALF + wr * 64 + m * 16 + fr; const float rs = S[r]; const size_t off = (size_t)(row_off + u.pm * BM + r) * DM + col0;
; #pragma unroll
;                 for (int bj = 0; bj < 2; ++bj)
; #pragma unroll
;                     for (int n = 0; n < 2; ++n) { const f32x4 bs = *(const f32x4*)(base + off + bj * HALF + n * 16); __builtin_nontemporal_store(bs + acc[ai][bj][m][n] * rs * g[bj][n], (f32x4*)(out + off + bj * HALF + n * 16)); }
.LBB0_1113:
	s_or_b64 exec, exec, s[10:11]
	s_lshl_b32 s6, s50, 12
	s_add_i32 s6, s51, s6
	s_ashr_i32 s7, s6, 31
	s_lshl_b64 s[6:7], s[6:7], 2
	s_add_u32 s6, s14, s6
	s_addc_u32 s7, s15, s7
	s_lshl_b32 s9, s16, 5
	s_lshl_b32 s10, s24, 8
	v_lshrrev_b32_e32 v128, 2, v138
	s_or_b32 s9, s10, s9
	v_and_or_b32 v128, v128, 12, s9
	s_waitcnt lgkmcnt(0)
	v_ashrrev_i32_e32 v129, 31, v128
	v_lshlrev_b64 v[150:151], 2, v[128:129]
	s_lshl_b32 s8, s50, 14
	v_lshl_add_u64 v[128:129], s[6:7], 0, v[150:151]
	s_lshl_b32 s6, s53, 8
	s_add_i32 s6, s6, s8
	v_add_u32_e32 v152, s6, v157
	v_ashrrev_i32_e32 v153, 31, v152
	v_lshl_add_u64 v[140:141], v[128:129], 0, s[22:23]
	v_add_co_u32_e32 v128, vcc, s49, v128
	v_lshlrev_b64 v[132:133], 12, v[152:153]
	v_add_u32_e32 v174, 16, v152
	s_waitcnt lgkmcnt(0)
	s_barrier
	s_mov_b32 s7, 0
	s_lshl_b64 s[6:7], s[6:7], 12
	s_add_u32 s6, s12, s6
	s_addc_u32 s7, s13, s7
	v_and_b32_e32 v136, 8, v157
	v_sub_u32_e32 v157, v157, v136
	v_lshlrev_b32_e32 v137, 3, v136
	v_lshl_add_u32 v144, v157, 2, 0
	v_add_u32_e32 v144, 0x1000, v144
	v_lshl_add_u32 v157, v157, 12, v150
	v_add_u32_e32 v157, v157, v137
	v_add_co_u32_e32 v140, vcc, v137, v140
	s_nop 1
	v_addc_co_u32_e32 v141, vcc, 0, v141, vcc
	global_load_dwordx4 v[128:131], v[140:141], off
	global_load_dwordx4 v[132:135], v[140:141], off offset:512
	ds_read2_b32 v[228:229], v144 offset0:0 offset1:8
	ds_read2_b32 v[230:231], v144 offset0:16 offset1:24
	ds_read2_b32 v[232:233], v144 offset0:32 offset1:40
	ds_read2_b32 v[234:235], v144 offset0:48 offset1:56
	ds_read2_b32 v[236:237], v144 offset0:128 offset1:136
	ds_read2_b32 v[238:239], v144 offset0:144 offset1:152
	ds_read2_b32 v[240:241], v144 offset0:160 offset1:168
	ds_read2_b32 v[242:243], v144 offset0:176 offset1:184
	v_mov_b32_e32 v252, v157
	v_add_u32_e32 v253, 0x8000, v157
	global_load_dwordx4 v[158:161], v252, s[6:7] nt
	global_load_dwordx4 v[162:165], v253, s[6:7] nt
	v_mov_b32_e32 v252, v157
	v_add_u32_e32 v253, 0x8000, v157
	global_load_dwordx4 v[166:169], v252, s[6:7] offset:512 nt
	global_load_dwordx4 v[170:173], v253, s[6:7] offset:512 nt
	v_add_u32_e32 v252, 0x10000, v157
	v_add_u32_e32 v253, 0x18000, v157
	global_load_dwordx4 v[174:177], v252, s[6:7] nt
	global_load_dwordx4 v[178:181], v253, s[6:7] nt
	v_add_u32_e32 v252, 0x10000, v157
	v_add_u32_e32 v253, 0x18000, v157
	global_load_dwordx4 v[182:185], v252, s[6:7] offset:512 nt
	global_load_dwordx4 v[186:189], v253, s[6:7] offset:512 nt
	v_add_u32_e32 v252, 0x20000, v157
	v_add_u32_e32 v253, 0x28000, v157
	global_load_dwordx4 v[196:199], v252, s[6:7] nt
	global_load_dwordx4 v[200:203], v253, s[6:7] nt
	v_add_u32_e32 v252, 0x20000, v157
	v_add_u32_e32 v253, 0x28000, v157
	global_load_dwordx4 v[204:207], v252, s[6:7] offset:512 nt
	global_load_dwordx4 v[208:211], v253, s[6:7] offset:512 nt
	v_add_u32_e32 v252, 0x30000, v157
	v_add_u32_e32 v253, 0x38000, v157
	global_load_dwordx4 v[212:215], v252, s[6:7] nt
	global_load_dwordx4 v[216:219], v253, s[6:7] nt
	v_add_u32_e32 v252, 0x30000, v157
	v_add_u32_e32 v253, 0x38000, v157
	global_load_dwordx4 v[220:223], v252, s[6:7] offset:512 nt
	global_load_dwordx4 v[224:227], v253, s[6:7] offset:512 nt
	s_waitcnt lgkmcnt(0)
	v_mov_b32_e32 v190, v124
	v_mov_b32_e32 v191, v125
	v_mov_b32_e32 v192, v126
	v_mov_b32_e32 v193, v127
	v_mov_b32_dpp v124, v120 row_ror:8 row_mask:0xf bank_mask:0xc
	v_mov_b32_dpp v125, v121 row_ror:8 row_mask:0xf bank_mask:0xc
	v_mov_b32_dpp v126, v122 row_ror:8 row_mask:0xf bank_mask:0xc
	v_mov_b32_dpp v127, v123 row_ror:8 row_mask:0xf bank_mask:0xc
	v_mov_b32_dpp v120, v190 row_ror:8 row_mask:0xf bank_mask:0x3
	v_mov_b32_dpp v121, v191 row_ror:8 row_mask:0xf bank_mask:0x3
	v_mov_b32_dpp v122, v192 row_ror:8 row_mask:0xf bank_mask:0x3
	v_mov_b32_dpp v123, v193 row_ror:8 row_mask:0xf bank_mask:0x3
	s_waitcnt vmcnt(14)
	v_mul_f32_e32 v124, v124, v228
	v_mul_f32_e32 v125, v125, v228
	v_mul_f32_e32 v126, v126, v228
	v_mul_f32_e32 v127, v127, v228
	v_mul_f32_e32 v120, v120, v229
	v_mul_f32_e32 v121, v121, v229
	v_mul_f32_e32 v122, v122, v229
	v_mul_f32_e32 v123, v123, v229
	v_fma_f32 v124, v124, v128, v158
	v_fma_f32 v125, v125, v129, v159
	v_fma_f32 v126, v126, v130, v160
	v_fma_f32 v127, v127, v131, v161
	v_fma_f32 v120, v120, v128, v162
	v_fma_f32 v121, v121, v129, v163
	v_fma_f32 v122, v122, v130, v164
	v_fma_f32 v123, v123, v131, v165
	v_mov_b32_e32 v252, v157
	v_add_u32_e32 v253, 0x8000, v157
	global_store_dwordx4 v252, v[124:127], s[6:7] nt
	global_store_dwordx4 v253, v[120:123], s[6:7] nt
	v_add_u32_e32 v252, 0x80000, v157
	v_add_u32_e32 v253, 0x88000, v157
	global_load_dwordx4 v[158:161], v252, s[6:7] nt
	global_load_dwordx4 v[162:165], v253, s[6:7] nt
	v_mov_b32_e32 v190, v108
	v_mov_b32_e32 v191, v109
	v_mov_b32_e32 v192, v110
	v_mov_b32_e32 v193, v111
	v_mov_b32_dpp v108, v104 row_ror:8 row_mask:0xf bank_mask:0xc
	v_mov_b32_dpp v109, v105 row_ror:8 row_mask:0xf bank_mask:0xc
	v_mov_b32_dpp v110, v106 row_ror:8 row_mask:0xf bank_mask:0xc
	v_mov_b32_dpp v111, v107 row_ror:8 row_mask:0xf bank_mask:0xc
	v_mov_b32_dpp v104, v190 row_ror:8 row_mask:0xf bank_mask:0x3
	v_mov_b32_dpp v105, v191 row_ror:8 row_mask:0xf bank_mask:0x3
	v_mov_b32_dpp v106, v192 row_ror:8 row_mask:0xf bank_mask:0x3
	v_mov_b32_dpp v107, v193 row_ror:8 row_mask:0xf bank_mask:0x3
	s_waitcnt vmcnt(16)
;     __device__ __forceinline__ void fused(f32x4 (&acc)[2][2][4][2], const Unit& u, int wr, int wc, int fr, int fq, PG8_LAS unsigned char* lds, int wid, int lane) const {
;     ...
;         for (int ai = 0; ai < 2; ++ai)
; #pragma unroll
;             for (int m = 0; m < 4; ++m) { const int r = ai * HALF + wr * 64 + m * 16 + fr; const float rs = S[r]; const size_t off = (size_t)(row_off + u.pm * BM + r) * DM + col0;
; #pragma unroll
;                 for (int bj = 0; bj < 2; ++bj)
; #pragma unroll
;                     for (int n = 0; n < 2; ++n) { const f32x4 bs = *(const f32x4*)(base + off + bj * HALF + n * 16); __builtin_nontemporal_store(bs + acc[ai][bj][m][n] * rs * g[bj][n], (f32x4*)(out + off + bj * HALF + n * 16)); }
;                 if (m & 1) asm volatile("" ::: "memory"); }
	v_mul_f32_e32 v108, v108, v228
	v_mul_f32_e32 v109, v109, v228
	v_mul_f32_e32 v110, v110, v228
	v_mul_f32_e32 v111, v111, v228
	v_mul_f32_e32 v104, v104, v229
	v_mul_f32_e32 v105, v105, v229
	v_mul_f32_e32 v106, v106, v229
	v_mul_f32_e32 v107, v107, v229
	v_fma_f32 v108, v108, v132, v166
	v_fma_f32 v109, v109, v133, v167
	v_fma_f32 v110, v110, v134, v168
	v_fma_f32 v111, v111, v135, v169
	v_fma_f32 v104, v104, v132, v170
	v_fma_f32 v105, v105, v133, v171
	v_fma_f32 v106, v106, v134, v172
	v_fma_f32 v107, v107, v135, v173
	v_mov_b32_e32 v252, v157
	v_add_u32_e32 v253, 0x8000, v157
	global_store_dwordx4 v252, v[108:111], s[6:7] offset:512 nt
	global_store_dwordx4 v253, v[104:107], s[6:7] offset:512 nt
	v_add_u32_e32 v252, 0x80000, v157
	v_add_u32_e32 v253, 0x88000, v157
	global_load_dwordx4 v[166:169], v252, s[6:7] offset:512 nt
	global_load_dwordx4 v[170:173], v253, s[6:7] offset:512 nt
	v_mov_b32_e32 v190, v116
	v_mov_b32_e32 v191, v117
	v_mov_b32_e32 v192, v118
	v_mov_b32_e32 v193, v119
	v_mov_b32_dpp v116, v112 row_ror:8 row_mask:0xf bank_mask:0xc
	v_mov_b32_dpp v117, v113 row_ror:8 row_mask:0xf bank_mask:0xc
	v_mov_b32_dpp v118, v114 row_ror:8 row_mask:0xf bank_mask:0xc
	v_mov_b32_dpp v119, v115 row_ror:8 row_mask:0xf bank_mask:0xc
	v_mov_b32_dpp v112, v190 row_ror:8 row_mask:0xf bank_mask:0x3
	v_mov_b32_dpp v113, v191 row_ror:8 row_mask:0xf bank_mask:0x3
	v_mov_b32_dpp v114, v192 row_ror:8 row_mask:0xf bank_mask:0x3
	v_mov_b32_dpp v115, v193 row_ror:8 row_mask:0xf bank_mask:0x3
	s_waitcnt vmcnt(18)
	v_mul_f32_e32 v116, v116, v230
	v_mul_f32_e32 v117, v117, v230
	v_mul_f32_e32 v118, v118, v230
	v_mul_f32_e32 v119, v119, v230
	v_mul_f32_e32 v112, v112, v231
	v_mul_f32_e32 v113, v113, v231
	v_mul_f32_e32 v114, v114, v231
	v_mul_f32_e32 v115, v115, v231
	v_fma_f32 v116, v116, v128, v174
	v_fma_f32 v117, v117, v129, v175
	v_fma_f32 v118, v118, v130, v176
	v_fma_f32 v119, v119, v131, v177
	v_fma_f32 v112, v112, v128, v178
	v_fma_f32 v113, v113, v129, v179
	v_fma_f32 v114, v114, v130, v180
	v_fma_f32 v115, v115, v131, v181
	v_add_u32_e32 v252, 0x10000, v157
	v_add_u32_e32 v253, 0x18000, v157
	global_store_dwordx4 v252, v[116:119], s[6:7] nt
	global_store_dwordx4 v253, v[112:115], s[6:7] nt
	v_add_u32_e32 v252, 0x90000, v157
	v_add_u32_e32 v253, 0x98000, v157
	global_load_dwordx4 v[174:177], v252, s[6:7] nt
	global_load_dwordx4 v[178:181], v253, s[6:7] nt
	v_mov_b32_e32 v190, v100
	v_mov_b32_e32 v191, v101
	v_mov_b32_e32 v192, v102
	v_mov_b32_e32 v193, v103
	v_mov_b32_dpp v100, v96 row_ror:8 row_mask:0xf bank_mask:0xc
	v_mov_b32_dpp v101, v97 row_ror:8 row_mask:0xf bank_mask:0xc
	v_mov_b32_dpp v102, v98 row_ror:8 row_mask:0xf bank_mask:0xc
	v_mov_b32_dpp v103, v99 row_ror:8 row_mask:0xf bank_mask:0xc
	v_mov_b32_dpp v96, v190 row_ror:8 row_mask:0xf bank_mask:0x3
	v_mov_b32_dpp v97, v191 row_ror:8 row_mask:0xf bank_mask:0x3
	v_mov_b32_dpp v98, v192 row_ror:8 row_mask:0xf bank_mask:0x3
	v_mov_b32_dpp v99, v193 row_ror:8 row_mask:0xf bank_mask:0x3
	s_waitcnt vmcnt(20)
	v_mul_f32_e32 v100, v100, v230
	v_mul_f32_e32 v101, v101, v230
	v_mul_f32_e32 v102, v102, v230
	v_mul_f32_e32 v103, v103, v230
	v_mul_f32_e32 v96, v96, v231
	v_mul_f32_e32 v97, v97, v231
	v_mul_f32_e32 v98, v98, v231
	v_mul_f32_e32 v99, v99, v231
	v_fma_f32 v100, v100, v132, v182
	v_fma_f32 v101, v101, v133, v183
	v_fma_f32 v102, v102, v134, v184
	v_fma_f32 v103, v103, v135, v185
	v_fma_f32 v96, v96, v132, v186
	v_fma_f32 v97, v97, v133, v187
	v_fma_f32 v98, v98, v134, v188
	v_fma_f32 v99, v99, v135, v189
	v_add_u32_e32 v252, 0x10000, v157
	v_add_u32_e32 v253, 0x18000, v157
	global_store_dwordx4 v252, v[100:103], s[6:7] offset:512 nt
	global_store_dwordx4 v253, v[96:99], s[6:7] offset:512 nt
	v_add_u32_e32 v252, 0x90000, v157
	v_add_u32_e32 v253, 0x98000, v157
	global_load_dwordx4 v[182:185], v252, s[6:7] offset:512 nt
	global_load_dwordx4 v[186:189], v253, s[6:7] offset:512 nt
	v_mov_b32_e32 v190, v92
	v_mov_b32_e32 v191, v93
	v_mov_b32_e32 v192, v94
	v_mov_b32_e32 v193, v95
	v_mov_b32_dpp v92, v88 row_ror:8 row_mask:0xf bank_mask:0xc
	v_mov_b32_dpp v93, v89 row_ror:8 row_mask:0xf bank_mask:0xc
	v_mov_b32_dpp v94, v90 row_ror:8 row_mask:0xf bank_mask:0xc
	v_mov_b32_dpp v95, v91 row_ror:8 row_mask:0xf bank_mask:0xc
	v_mov_b32_dpp v88, v190 row_ror:8 row_mask:0xf bank_mask:0x3
	v_mov_b32_dpp v89, v191 row_ror:8 row_mask:0xf bank_mask:0x3
	v_mov_b32_dpp v90, v192 row_ror:8 row_mask:0xf bank_mask:0x3
	v_mov_b32_dpp v91, v193 row_ror:8 row_mask:0xf bank_mask:0x3
	s_waitcnt vmcnt(22)
	v_mul_f32_e32 v92, v92, v232
	v_mul_f32_e32 v93, v93, v232
	v_mul_f32_e32 v94, v94, v232
	v_mul_f32_e32 v95, v95, v232
	v_mul_f32_e32 v88, v88, v233
	v_mul_f32_e32 v89, v89, v233
	v_mul_f32_e32 v90, v90, v233
	v_mul_f32_e32 v91, v91, v233
	v_fma_f32 v92, v92, v128, v196
	v_fma_f32 v93, v93, v129, v197
	v_fma_f32 v94, v94, v130, v198
	v_fma_f32 v95, v95, v131, v199
	v_fma_f32 v88, v88, v128, v200
	v_fma_f32 v89, v89, v129, v201
	v_fma_f32 v90, v90, v130, v202
	v_fma_f32 v91, v91, v131, v203
	v_add_u32_e32 v252, 0x20000, v157
	v_add_u32_e32 v253, 0x28000, v157
	global_store_dwordx4 v252, v[92:95], s[6:7] nt
	global_store_dwordx4 v253, v[88:91], s[6:7] nt
	v_add_u32_e32 v252, 0xa0000, v157
	v_add_u32_e32 v253, 0xa8000, v157
	global_load_dwordx4 v[196:199], v252, s[6:7] nt
	global_load_dwordx4 v[200:203], v253, s[6:7] nt
	v_mov_b32_e32 v190, v76
	v_mov_b32_e32 v191, v77
	v_mov_b32_e32 v192, v78
	v_mov_b32_e32 v193, v79
	v_mov_b32_dpp v76, v72 row_ror:8 row_mask:0xf bank_mask:0xc
	v_mov_b32_dpp v77, v73 row_ror:8 row_mask:0xf bank_mask:0xc
	v_mov_b32_dpp v78, v74 row_ror:8 row_mask:0xf bank_mask:0xc
	v_mov_b32_dpp v79, v75 row_ror:8 row_mask:0xf bank_mask:0xc
	v_mov_b32_dpp v72, v190 row_ror:8 row_mask:0xf bank_mask:0x3
	v_mov_b32_dpp v73, v191 row_ror:8 row_mask:0xf bank_mask:0x3
	v_mov_b32_dpp v74, v192 row_ror:8 row_mask:0xf bank_mask:0x3
	v_mov_b32_dpp v75, v193 row_ror:8 row_mask:0xf bank_mask:0x3
	s_waitcnt vmcnt(24)
;     __device__ __forceinline__ void fused(f32x4 (&acc)[2][2][4][2], const Unit& u, int wr, int wc, int fr, int fq, PG8_LAS unsigned char* lds, int wid, int lane) const {
;     ...
;         for (int ai = 0; ai < 2; ++ai)
; #pragma unroll
;             for (int m = 0; m < 4; ++m) { const int r = ai * HALF + wr * 64 + m * 16 + fr; const float rs = S[r]; const size_t off = (size_t)(row_off + u.pm * BM + r) * DM + col0;
; #pragma unroll
;                 for (int bj = 0; bj < 2; ++bj)
; #pragma unroll
;                     for (int n = 0; n < 2; ++n) { const f32x4 bs = *(const f32x4*)(base + off + bj * HALF + n * 16); __builtin_nontemporal_store(bs + acc[ai][bj][m][n] * rs * g[bj][n], (f32x4*)(out + off + bj * HALF + n * 16)); }
;                 if (m & 1) asm volatile("" ::: "memory"); }
	v_mul_f32_e32 v76, v76, v232
	v_mul_f32_e32 v77, v77, v232
	v_mul_f32_e32 v78, v78, v232
	v_mul_f32_e32 v79, v79, v232
	v_mul_f32_e32 v72, v72, v233
	v_mul_f32_e32 v73, v73, v233
	v_mul_f32_e32 v74, v74, v233
	v_mul_f32_e32 v75, v75, v233
	v_fma_f32 v76, v76, v132, v204
	v_fma_f32 v77, v77, v133, v205
	v_fma_f32 v78, v78, v134, v206
	v_fma_f32 v79, v79, v135, v207
	v_fma_f32 v72, v72, v132, v208
	v_fma_f32 v73, v73, v133, v209
	v_fma_f32 v74, v74, v134, v210
	v_fma_f32 v75, v75, v135, v211
	v_add_u32_e32 v252, 0x20000, v157
	v_add_u32_e32 v253, 0x28000, v157
	global_store_dwordx4 v252, v[76:79], s[6:7] offset:512 nt
	global_store_dwordx4 v253, v[72:75], s[6:7] offset:512 nt
	v_add_u32_e32 v252, 0xa0000, v157
	v_add_u32_e32 v253, 0xa8000, v157
	global_load_dwordx4 v[204:207], v252, s[6:7] offset:512 nt
	global_load_dwordx4 v[208:211], v253, s[6:7] offset:512 nt
	v_mov_b32_e32 v190, v84
	v_mov_b32_e32 v191, v85
	v_mov_b32_e32 v192, v86
	v_mov_b32_e32 v193, v87
	v_mov_b32_dpp v84, v80 row_ror:8 row_mask:0xf bank_mask:0xc
	v_mov_b32_dpp v85, v81 row_ror:8 row_mask:0xf bank_mask:0xc
	v_mov_b32_dpp v86, v82 row_ror:8 row_mask:0xf bank_mask:0xc
	v_mov_b32_dpp v87, v83 row_ror:8 row_mask:0xf bank_mask:0xc
	v_mov_b32_dpp v80, v190 row_ror:8 row_mask:0xf bank_mask:0x3
	v_mov_b32_dpp v81, v191 row_ror:8 row_mask:0xf bank_mask:0x3
	v_mov_b32_dpp v82, v192 row_ror:8 row_mask:0xf bank_mask:0x3
	v_mov_b32_dpp v83, v193 row_ror:8 row_mask:0xf bank_mask:0x3
	s_waitcnt vmcnt(26)
	v_mul_f32_e32 v84, v84, v234
	v_mul_f32_e32 v85, v85, v234
	v_mul_f32_e32 v86, v86, v234
	v_mul_f32_e32 v87, v87, v234
	v_mul_f32_e32 v80, v80, v235
	v_mul_f32_e32 v81, v81, v235
	v_mul_f32_e32 v82, v82, v235
	v_mul_f32_e32 v83, v83, v235
	v_fma_f32 v84, v84, v128, v212
	v_fma_f32 v85, v85, v129, v213
	v_fma_f32 v86, v86, v130, v214
	v_fma_f32 v87, v87, v131, v215
	v_fma_f32 v80, v80, v128, v216
	v_fma_f32 v81, v81, v129, v217
	v_fma_f32 v82, v82, v130, v218
	v_fma_f32 v83, v83, v131, v219
	v_add_u32_e32 v252, 0x30000, v157
	v_add_u32_e32 v253, 0x38000, v157
	global_store_dwordx4 v252, v[84:87], s[6:7] nt
	global_store_dwordx4 v253, v[80:83], s[6:7] nt
	v_add_u32_e32 v252, 0xb0000, v157
	v_add_u32_e32 v253, 0xb8000, v157
	global_load_dwordx4 v[212:215], v252, s[6:7] nt
	global_load_dwordx4 v[216:219], v253, s[6:7] nt
	v_mov_b32_e32 v190, v68
	v_mov_b32_e32 v191, v69
	v_mov_b32_e32 v192, v70
	v_mov_b32_e32 v193, v71
	v_mov_b32_dpp v68, v64 row_ror:8 row_mask:0xf bank_mask:0xc
	v_mov_b32_dpp v69, v65 row_ror:8 row_mask:0xf bank_mask:0xc
	v_mov_b32_dpp v70, v66 row_ror:8 row_mask:0xf bank_mask:0xc
	v_mov_b32_dpp v71, v67 row_ror:8 row_mask:0xf bank_mask:0xc
	v_mov_b32_dpp v64, v190 row_ror:8 row_mask:0xf bank_mask:0x3
	v_mov_b32_dpp v65, v191 row_ror:8 row_mask:0xf bank_mask:0x3
	v_mov_b32_dpp v66, v192 row_ror:8 row_mask:0xf bank_mask:0x3
	v_mov_b32_dpp v67, v193 row_ror:8 row_mask:0xf bank_mask:0x3
	s_waitcnt vmcnt(28)
	v_mul_f32_e32 v68, v68, v234
	v_mul_f32_e32 v69, v69, v234
	v_mul_f32_e32 v70, v70, v234
	v_mul_f32_e32 v71, v71, v234
	v_mul_f32_e32 v64, v64, v235
	v_mul_f32_e32 v65, v65, v235
	v_mul_f32_e32 v66, v66, v235
	v_mul_f32_e32 v67, v67, v235
	v_fma_f32 v68, v68, v132, v220
	v_fma_f32 v69, v69, v133, v221
	v_fma_f32 v70, v70, v134, v222
	v_fma_f32 v71, v71, v135, v223
	v_fma_f32 v64, v64, v132, v224
	v_fma_f32 v65, v65, v133, v225
	v_fma_f32 v66, v66, v134, v226
	v_fma_f32 v67, v67, v135, v227
	v_add_u32_e32 v252, 0x30000, v157
	v_add_u32_e32 v253, 0x38000, v157
	global_store_dwordx4 v252, v[68:71], s[6:7] offset:512 nt
	global_store_dwordx4 v253, v[64:67], s[6:7] offset:512 nt
	v_add_u32_e32 v252, 0xb0000, v157
	v_add_u32_e32 v253, 0xb8000, v157
	global_load_dwordx4 v[220:223], v252, s[6:7] offset:512 nt
	global_load_dwordx4 v[224:227], v253, s[6:7] offset:512 nt
	v_mov_b32_e32 v190, v60
	v_mov_b32_e32 v191, v61
	v_mov_b32_e32 v192, v62
	v_mov_b32_e32 v193, v63
	v_mov_b32_dpp v60, v56 row_ror:8 row_mask:0xf bank_mask:0xc
	v_mov_b32_dpp v61, v57 row_ror:8 row_mask:0xf bank_mask:0xc
	v_mov_b32_dpp v62, v58 row_ror:8 row_mask:0xf bank_mask:0xc
	v_mov_b32_dpp v63, v59 row_ror:8 row_mask:0xf bank_mask:0xc
	v_mov_b32_dpp v56, v190 row_ror:8 row_mask:0xf bank_mask:0x3
	v_mov_b32_dpp v57, v191 row_ror:8 row_mask:0xf bank_mask:0x3
	v_mov_b32_dpp v58, v192 row_ror:8 row_mask:0xf bank_mask:0x3
	v_mov_b32_dpp v59, v193 row_ror:8 row_mask:0xf bank_mask:0x3
	s_waitcnt vmcnt(28)
	v_mul_f32_e32 v60, v60, v236
	v_mul_f32_e32 v61, v61, v236
	v_mul_f32_e32 v62, v62, v236
	v_mul_f32_e32 v63, v63, v236
	v_mul_f32_e32 v56, v56, v237
	v_mul_f32_e32 v57, v57, v237
	v_mul_f32_e32 v58, v58, v237
	v_mul_f32_e32 v59, v59, v237
	v_fma_f32 v60, v60, v128, v158
	v_fma_f32 v61, v61, v129, v159
	v_fma_f32 v62, v62, v130, v160
	v_fma_f32 v63, v63, v131, v161
	v_fma_f32 v56, v56, v128, v162
	v_fma_f32 v57, v57, v129, v163
	v_fma_f32 v58, v58, v130, v164
	v_fma_f32 v59, v59, v131, v165
	v_add_u32_e32 v252, 0x80000, v157
	v_add_u32_e32 v253, 0x88000, v157
	global_store_dwordx4 v252, v[60:63], s[6:7] nt
	global_store_dwordx4 v253, v[56:59], s[6:7] nt
	v_mov_b32_e32 v190, v44
	v_mov_b32_e32 v191, v45
	v_mov_b32_e32 v192, v46
	v_mov_b32_e32 v193, v47
	v_mov_b32_dpp v44, v40 row_ror:8 row_mask:0xf bank_mask:0xc
	v_mov_b32_dpp v45, v41 row_ror:8 row_mask:0xf bank_mask:0xc
	v_mov_b32_dpp v46, v42 row_ror:8 row_mask:0xf bank_mask:0xc
	v_mov_b32_dpp v47, v43 row_ror:8 row_mask:0xf bank_mask:0xc
	v_mov_b32_dpp v40, v190 row_ror:8 row_mask:0xf bank_mask:0x3
	v_mov_b32_dpp v41, v191 row_ror:8 row_mask:0xf bank_mask:0x3
	v_mov_b32_dpp v42, v192 row_ror:8 row_mask:0xf bank_mask:0x3
	v_mov_b32_dpp v43, v193 row_ror:8 row_mask:0xf bank_mask:0x3
	s_waitcnt vmcnt(26)
;     __device__ __forceinline__ void fused(f32x4 (&acc)[2][2][4][2], const Unit& u, int wr, int wc, int fr, int fq, PG8_LAS unsigned char* lds, int wid, int lane) const {
;     ...
;         for (int ai = 0; ai < 2; ++ai)
; #pragma unroll
;             for (int m = 0; m < 4; ++m) { const int r = ai * HALF + wr * 64 + m * 16 + fr; const float rs = S[r]; const size_t off = (size_t)(row_off + u.pm * BM + r) * DM + col0;
; #pragma unroll
;                 for (int bj = 0; bj < 2; ++bj)
; #pragma unroll
;                     for (int n = 0; n < 2; ++n) { const f32x4 bs = *(const f32x4*)(base + off + bj * HALF + n * 16); __builtin_nontemporal_store(bs + acc[ai][bj][m][n] * rs * g[bj][n], (f32x4*)(out + off + bj * HALF + n * 16)); }
;                 if (m & 1) asm volatile("" ::: "memory"); }
	v_mul_f32_e32 v44, v44, v236
	v_mul_f32_e32 v45, v45, v236
	v_mul_f32_e32 v46, v46, v236
	v_mul_f32_e32 v47, v47, v236
	v_mul_f32_e32 v40, v40, v237
	v_mul_f32_e32 v41, v41, v237
	v_mul_f32_e32 v42, v42, v237
	v_mul_f32_e32 v43, v43, v237
	v_fma_f32 v44, v44, v132, v166
	v_fma_f32 v45, v45, v133, v167
	v_fma_f32 v46, v46, v134, v168
	v_fma_f32 v47, v47, v135, v169
	v_fma_f32 v40, v40, v132, v170
	v_fma_f32 v41, v41, v133, v171
	v_fma_f32 v42, v42, v134, v172
	v_fma_f32 v43, v43, v135, v173
	v_add_u32_e32 v252, 0x80000, v157
	v_add_u32_e32 v253, 0x88000, v157
	global_store_dwordx4 v252, v[44:47], s[6:7] offset:512 nt
	global_store_dwordx4 v253, v[40:43], s[6:7] offset:512 nt
	v_mov_b32_e32 v190, v52
	v_mov_b32_e32 v191, v53
	v_mov_b32_e32 v192, v54
	v_mov_b32_e32 v193, v55
	v_mov_b32_dpp v52, v48 row_ror:8 row_mask:0xf bank_mask:0xc
	v_mov_b32_dpp v53, v49 row_ror:8 row_mask:0xf bank_mask:0xc
	v_mov_b32_dpp v54, v50 row_ror:8 row_mask:0xf bank_mask:0xc
	v_mov_b32_dpp v55, v51 row_ror:8 row_mask:0xf bank_mask:0xc
	v_mov_b32_dpp v48, v190 row_ror:8 row_mask:0xf bank_mask:0x3
	v_mov_b32_dpp v49, v191 row_ror:8 row_mask:0xf bank_mask:0x3
	v_mov_b32_dpp v50, v192 row_ror:8 row_mask:0xf bank_mask:0x3
	v_mov_b32_dpp v51, v193 row_ror:8 row_mask:0xf bank_mask:0x3
	s_waitcnt vmcnt(24)
	v_mul_f32_e32 v52, v52, v238
	v_mul_f32_e32 v53, v53, v238
	v_mul_f32_e32 v54, v54, v238
	v_mul_f32_e32 v55, v55, v238
	v_mul_f32_e32 v48, v48, v239
	v_mul_f32_e32 v49, v49, v239
	v_mul_f32_e32 v50, v50, v239
	v_mul_f32_e32 v51, v51, v239
	v_fma_f32 v52, v52, v128, v174
	v_fma_f32 v53, v53, v129, v175
	v_fma_f32 v54, v54, v130, v176
	v_fma_f32 v55, v55, v131, v177
	v_fma_f32 v48, v48, v128, v178
	v_fma_f32 v49, v49, v129, v179
	v_fma_f32 v50, v50, v130, v180
	v_fma_f32 v51, v51, v131, v181
	v_add_u32_e32 v252, 0x90000, v157
	v_add_u32_e32 v253, 0x98000, v157
	global_store_dwordx4 v252, v[52:55], s[6:7] nt
	global_store_dwordx4 v253, v[48:51], s[6:7] nt
	v_mov_b32_e32 v190, v36
	v_mov_b32_e32 v191, v37
	v_mov_b32_e32 v192, v38
	v_mov_b32_e32 v193, v39
	v_mov_b32_dpp v36, v32 row_ror:8 row_mask:0xf bank_mask:0xc
	v_mov_b32_dpp v37, v33 row_ror:8 row_mask:0xf bank_mask:0xc
	v_mov_b32_dpp v38, v34 row_ror:8 row_mask:0xf bank_mask:0xc
	v_mov_b32_dpp v39, v35 row_ror:8 row_mask:0xf bank_mask:0xc
	v_mov_b32_dpp v32, v190 row_ror:8 row_mask:0xf bank_mask:0x3
	v_mov_b32_dpp v33, v191 row_ror:8 row_mask:0xf bank_mask:0x3
	v_mov_b32_dpp v34, v192 row_ror:8 row_mask:0xf bank_mask:0x3
	v_mov_b32_dpp v35, v193 row_ror:8 row_mask:0xf bank_mask:0x3
	s_waitcnt vmcnt(22)
	v_mul_f32_e32 v36, v36, v238
	v_mul_f32_e32 v37, v37, v238
	v_mul_f32_e32 v38, v38, v238
	v_mul_f32_e32 v39, v39, v238
	v_mul_f32_e32 v32, v32, v239
	v_mul_f32_e32 v33, v33, v239
	v_mul_f32_e32 v34, v34, v239
	v_mul_f32_e32 v35, v35, v239
	v_fma_f32 v36, v36, v132, v182
	v_fma_f32 v37, v37, v133, v183
	v_fma_f32 v38, v38, v134, v184
	v_fma_f32 v39, v39, v135, v185
	v_fma_f32 v32, v32, v132, v186
	v_fma_f32 v33, v33, v133, v187
	v_fma_f32 v34, v34, v134, v188
	v_fma_f32 v35, v35, v135, v189
	v_add_u32_e32 v252, 0x90000, v157
	v_add_u32_e32 v253, 0x98000, v157
	global_store_dwordx4 v252, v[36:39], s[6:7] offset:512 nt
	global_store_dwordx4 v253, v[32:35], s[6:7] offset:512 nt
	v_mov_b32_e32 v190, v28
	v_mov_b32_e32 v191, v29
	v_mov_b32_e32 v192, v30
	v_mov_b32_e32 v193, v31
	v_mov_b32_dpp v28, v24 row_ror:8 row_mask:0xf bank_mask:0xc
	v_mov_b32_dpp v29, v25 row_ror:8 row_mask:0xf bank_mask:0xc
	v_mov_b32_dpp v30, v26 row_ror:8 row_mask:0xf bank_mask:0xc
	v_mov_b32_dpp v31, v27 row_ror:8 row_mask:0xf bank_mask:0xc
	v_mov_b32_dpp v24, v190 row_ror:8 row_mask:0xf bank_mask:0x3
	v_mov_b32_dpp v25, v191 row_ror:8 row_mask:0xf bank_mask:0x3
	v_mov_b32_dpp v26, v192 row_ror:8 row_mask:0xf bank_mask:0x3
	v_mov_b32_dpp v27, v193 row_ror:8 row_mask:0xf bank_mask:0x3
	s_waitcnt vmcnt(20)
;     __device__ __forceinline__ void fused(f32x4 (&acc)[2][2][4][2], const Unit& u, int wr, int wc, int fr, int fq, PG8_LAS unsigned char* lds, int wid, int lane) const {
;     ...
;         for (int ai = 0; ai < 2; ++ai)
; #pragma unroll
;             for (int m = 0; m < 4; ++m) { const int r = ai * HALF + wr * 64 + m * 16 + fr; const float rs = S[r]; const size_t off = (size_t)(row_off + u.pm * BM + r) * DM + col0;
; #pragma unroll
;                 for (int bj = 0; bj < 2; ++bj)
; #pragma unroll
;                     for (int n = 0; n < 2; ++n) { const f32x4 bs = *(const f32x4*)(base + off + bj * HALF + n * 16); __builtin_nontemporal_store(bs + acc[ai][bj][m][n] * rs * g[bj][n], (f32x4*)(out + off + bj * HALF + n * 16)); }
;                 if (m & 1) asm volatile("" ::: "memory"); }
;         asm volatile("s_waitcnt lgkmcnt(0)" ::: "memory"); __builtin_amdgcn_s_barrier(); asm volatile("" ::: "memory");
	v_mul_f32_e32 v28, v28, v240
	v_mul_f32_e32 v29, v29, v240
	v_mul_f32_e32 v30, v30, v240
	v_mul_f32_e32 v31, v31, v240
	v_mul_f32_e32 v24, v24, v241
	v_mul_f32_e32 v25, v25, v241
	v_mul_f32_e32 v26, v26, v241
	v_mul_f32_e32 v27, v27, v241
	v_fma_f32 v28, v28, v128, v196
	v_fma_f32 v29, v29, v129, v197
	v_fma_f32 v30, v30, v130, v198
	v_fma_f32 v31, v31, v131, v199
	v_fma_f32 v24, v24, v128, v200
	v_fma_f32 v25, v25, v129, v201
	v_fma_f32 v26, v26, v130, v202
	v_fma_f32 v27, v27, v131, v203
	v_add_u32_e32 v252, 0xa0000, v157
	v_add_u32_e32 v253, 0xa8000, v157
	global_store_dwordx4 v252, v[28:31], s[6:7] nt
	global_store_dwordx4 v253, v[24:27], s[6:7] nt
	v_mov_b32_e32 v190, v12
	v_mov_b32_e32 v191, v13
	v_mov_b32_e32 v192, v14
	v_mov_b32_e32 v193, v15
	v_mov_b32_dpp v12, v8 row_ror:8 row_mask:0xf bank_mask:0xc
	v_mov_b32_dpp v13, v9 row_ror:8 row_mask:0xf bank_mask:0xc
	v_mov_b32_dpp v14, v10 row_ror:8 row_mask:0xf bank_mask:0xc
	v_mov_b32_dpp v15, v11 row_ror:8 row_mask:0xf bank_mask:0xc
	v_mov_b32_dpp v8, v190 row_ror:8 row_mask:0xf bank_mask:0x3
	v_mov_b32_dpp v9, v191 row_ror:8 row_mask:0xf bank_mask:0x3
	v_mov_b32_dpp v10, v192 row_ror:8 row_mask:0xf bank_mask:0x3
	v_mov_b32_dpp v11, v193 row_ror:8 row_mask:0xf bank_mask:0x3
	s_waitcnt vmcnt(18)
	v_mul_f32_e32 v12, v12, v240
	v_mul_f32_e32 v13, v13, v240
	v_mul_f32_e32 v14, v14, v240
	v_mul_f32_e32 v15, v15, v240
	v_mul_f32_e32 v8, v8, v241
	v_mul_f32_e32 v9, v9, v241
	v_mul_f32_e32 v10, v10, v241
	v_mul_f32_e32 v11, v11, v241
	v_fma_f32 v12, v12, v132, v204
	v_fma_f32 v13, v13, v133, v205
	v_fma_f32 v14, v14, v134, v206
	v_fma_f32 v15, v15, v135, v207
	v_fma_f32 v8, v8, v132, v208
	v_fma_f32 v9, v9, v133, v209
	v_fma_f32 v10, v10, v134, v210
	v_fma_f32 v11, v11, v135, v211
	v_add_u32_e32 v252, 0xa0000, v157
	v_add_u32_e32 v253, 0xa8000, v157
	global_store_dwordx4 v252, v[12:15], s[6:7] offset:512 nt
	global_store_dwordx4 v253, v[8:11], s[6:7] offset:512 nt
	v_mov_b32_e32 v190, v20
	v_mov_b32_e32 v191, v21
	v_mov_b32_e32 v192, v22
	v_mov_b32_e32 v193, v23
	v_mov_b32_dpp v20, v16 row_ror:8 row_mask:0xf bank_mask:0xc
	v_mov_b32_dpp v21, v17 row_ror:8 row_mask:0xf bank_mask:0xc
	v_mov_b32_dpp v22, v18 row_ror:8 row_mask:0xf bank_mask:0xc
	v_mov_b32_dpp v23, v19 row_ror:8 row_mask:0xf bank_mask:0xc
	v_mov_b32_dpp v16, v190 row_ror:8 row_mask:0xf bank_mask:0x3
	v_mov_b32_dpp v17, v191 row_ror:8 row_mask:0xf bank_mask:0x3
	v_mov_b32_dpp v18, v192 row_ror:8 row_mask:0xf bank_mask:0x3
	v_mov_b32_dpp v19, v193 row_ror:8 row_mask:0xf bank_mask:0x3
	s_waitcnt vmcnt(16)
	v_mul_f32_e32 v20, v20, v242
	v_mul_f32_e32 v21, v21, v242
	v_mul_f32_e32 v22, v22, v242
	v_mul_f32_e32 v23, v23, v242
	v_mul_f32_e32 v16, v16, v243
	v_mul_f32_e32 v17, v17, v243
	v_mul_f32_e32 v18, v18, v243
	v_mul_f32_e32 v19, v19, v243
	v_fma_f32 v20, v20, v128, v212
	v_fma_f32 v21, v21, v129, v213
	v_fma_f32 v22, v22, v130, v214
	v_fma_f32 v23, v23, v131, v215
	v_fma_f32 v16, v16, v128, v216
	v_fma_f32 v17, v17, v129, v217
	v_fma_f32 v18, v18, v130, v218
	v_fma_f32 v19, v19, v131, v219
	v_add_u32_e32 v252, 0xb0000, v157
	v_add_u32_e32 v253, 0xb8000, v157
	global_store_dwordx4 v252, v[20:23], s[6:7] nt
	global_store_dwordx4 v253, v[16:19], s[6:7] nt
	v_mov_b32_e32 v190, v4
	v_mov_b32_e32 v191, v5
	v_mov_b32_e32 v192, v6
	v_mov_b32_e32 v193, v7
	v_mov_b32_dpp v4, v0 row_ror:8 row_mask:0xf bank_mask:0xc
	v_mov_b32_dpp v5, v1 row_ror:8 row_mask:0xf bank_mask:0xc
	v_mov_b32_dpp v6, v2 row_ror:8 row_mask:0xf bank_mask:0xc
	v_mov_b32_dpp v7, v3 row_ror:8 row_mask:0xf bank_mask:0xc
	v_mov_b32_dpp v0, v190 row_ror:8 row_mask:0xf bank_mask:0x3
	v_mov_b32_dpp v1, v191 row_ror:8 row_mask:0xf bank_mask:0x3
	v_mov_b32_dpp v2, v192 row_ror:8 row_mask:0xf bank_mask:0x3
	v_mov_b32_dpp v3, v193 row_ror:8 row_mask:0xf bank_mask:0x3
	s_waitcnt vmcnt(14)
	v_mul_f32_e32 v4, v4, v242
	v_mul_f32_e32 v5, v5, v242
	v_mul_f32_e32 v6, v6, v242
	v_mul_f32_e32 v7, v7, v242
	v_mul_f32_e32 v0, v0, v243
	v_mul_f32_e32 v1, v1, v243
	v_mul_f32_e32 v2, v2, v243
	v_mul_f32_e32 v3, v3, v243
	v_fma_f32 v4, v4, v132, v220
	v_fma_f32 v5, v5, v133, v221
	v_fma_f32 v6, v6, v134, v222
	v_fma_f32 v7, v7, v135, v223
	v_fma_f32 v0, v0, v132, v224
	v_fma_f32 v1, v1, v133, v225
	v_fma_f32 v2, v2, v134, v226
	v_fma_f32 v3, v3, v135, v227
	v_add_u32_e32 v252, 0xb0000, v157
	v_add_u32_e32 v253, 0xb8000, v157
	global_store_dwordx4 v252, v[4:7], s[6:7] offset:512 nt
	global_store_dwordx4 v253, v[0:3], s[6:7] offset:512 nt
	s_waitcnt lgkmcnt(0)
	s_barrier
